# pool_item (latent) window sums: per-element ds_read+wait+add loops replaced by one pipelined read of the needed rows and register sums in the same order (one straight-line variant per window size)
# speedup vs baseline: 1.0187x; 1.0048x over previous
; DI void pool_item(const Params& p, int layer, int seq, int tile, int g, char* smem) {
;     ...
;             const int c = tid + THREADS * i, rr = c >> 3, c8 = (c & 7) * 8;
;             if (c < 640) { float f[8]; unpack8(uch[i], f);
; #pragma unroll
;                 for (int j = 0; j < 8; ++j) su[rr * 64 + c8 + j] = f[j]; }
;         }
; #pragma unroll
;         for (int i = 0; i < 16; ++i) sw[tid + THREADS * i] = wv[i];
;     }
;     __syncthreads();
;     const int e = tid & 63, tq = tid >> 6;
; #pragma unroll 4
;     for (int i = 0; i < 16; ++i) {
;         const int tt = tq * 16 + i, t = t0 + tt;
;         const int lo = t - w2 < 0 ? 0 : t - w2, hi = t + w2 > Ls ? Ls : t + w2;
;         float s = 0.f;
;         for (int q = lo; q < hi; ++q) s += su[(q - t0 + 8) * 64 + e];
;         sd[tt * 68 + e] = s * __builtin_amdgcn_rcpf((float)(hi - lo)) - su[(tt + 8) * 64 + e];
.LBB0_286:
	s_or_b64 exec, exec, s[0:1]
	v_lshl_add_u32 v0, v12, 2, s25
	v_ashrrev_i32_e32 v3, 2, v12
	s_and_b32 s0, s22, 0x7f
	s_waitcnt vmcnt(14)
	ds_write2st64_b32 v0, v13, v14 offset0:148 offset1:152
	s_waitcnt vmcnt(12)
	ds_write2st64_b32 v0, v15, v20 offset0:156 offset1:160
	s_waitcnt vmcnt(10)
	ds_write2st64_b32 v0, v21, v22 offset0:164 offset1:168
	s_waitcnt vmcnt(8)
	ds_write2st64_b32 v0, v23, v24 offset0:172 offset1:176
	s_waitcnt vmcnt(6)
	ds_write2st64_b32 v0, v25, v26 offset0:180 offset1:184
	s_waitcnt vmcnt(4)
	ds_write2st64_b32 v0, v27, v28 offset0:188 offset1:192
	s_waitcnt vmcnt(2)
	ds_write2st64_b32 v0, v29, v30 offset0:196 offset1:200
	s_waitcnt vmcnt(0)
	ds_write2st64_b32 v0, v31, v32 offset0:204 offset1:208
	v_and_b32_e32 v30, 63, v12
	v_and_b32_e32 v2, -16, v3
	s_lshl_b32 s1, s0, 14
	s_lshl_b32 s6, 1, s21
	v_lshlrev_b32_e32 v1, 2, v30
	v_lshl_add_u32 v8, s0, 6, v2
	v_subrev_u32_e32 v4, s1, v1
	v_subrev_u32_e32 v5, s6, v8
	v_or_b32_e32 v6, 1, v8
	v_or_b32_e32 v7, 2, v8
	v_or_b32_e32 v8, 3, v8
	v_add_u32_e32 v0, s25, v1
	v_add_u32_e32 v4, s15, v4
	v_subrev_u32_e32 v6, s6, v6
	v_subrev_u32_e32 v7, s6, v7
	v_subrev_u32_e32 v8, s6, v8
	s_mov_b32 s7, 0
	s_waitcnt lgkmcnt(0)
	s_barrier
	s_cmp_eq_u32 s21, 3
	s_cbranch_scc1 .Lpw_g3
	s_cmp_eq_u32 s21, 2
	s_cbranch_scc1 .Lpw_g2
	s_cmp_eq_u32 s21, 1
	s_cbranch_scc1 .Lpw_g1
	v_lshl_add_u32 v71, v2, 8, v0
	ds_read_b32 v47, v71 offset:1792
	ds_read_b32 v48, v71 offset:2048
	ds_read_b32 v49, v71 offset:2304
	ds_read_b32 v50, v71 offset:2560
	ds_read_b32 v51, v71 offset:2816
	ds_read_b32 v52, v71 offset:3072
	ds_read_b32 v53, v71 offset:3328
	ds_read_b32 v54, v71 offset:3584
	ds_read_b32 v55, v71 offset:3840
	ds_read_b32 v56, v71 offset:4096
	ds_read_b32 v57, v71 offset:4352
	ds_read_b32 v58, v71 offset:4608
	ds_read_b32 v59, v71 offset:4864
	ds_read_b32 v60, v71 offset:5120
	ds_read_b32 v61, v71 offset:5376
	ds_read_b32 v62, v71 offset:5632
	ds_read_b32 v63, v71 offset:5888
	v_mad_u32_u24 v72, v2, s30, v0
	v_add_u32_e32 v73, s26, v2
	s_waitcnt lgkmcnt(0)
	v_subrev_u32_e32 v75, s6, v73
	v_add_u32_e32 v76, s6, v73
	v_max_i32_e32 v75, 0, v75
	v_min_i32_e32 v76, 0x2000, v76
	v_sub_u32_e32 v75, v76, v75
	v_cvt_f32_i32_e32 v75, v75
	v_rcp_iflag_f32_e32 v75, v75
	v_add_f32_e32 v77, 0, v47
	v_add_f32_e32 v77, v77, v48
	v_fma_f32 v77, v75, v77, -v48
	ds_write_b32 v72, v77 offset:20480
	v_add_u32_e32 v74, 1, v73
	v_subrev_u32_e32 v75, s6, v74
	v_add_u32_e32 v76, s6, v74
	v_max_i32_e32 v75, 0, v75
	v_min_i32_e32 v76, 0x2000, v76
	v_sub_u32_e32 v75, v76, v75
	v_cvt_f32_i32_e32 v75, v75
	v_rcp_iflag_f32_e32 v75, v75
	v_add_f32_e32 v77, 0, v48
	v_add_f32_e32 v77, v77, v49
	v_fma_f32 v77, v75, v77, -v49
	ds_write_b32 v72, v77 offset:20752
	v_add_u32_e32 v74, 2, v73
	v_subrev_u32_e32 v75, s6, v74
	v_add_u32_e32 v76, s6, v74
	v_max_i32_e32 v75, 0, v75
	v_min_i32_e32 v76, 0x2000, v76
	v_sub_u32_e32 v75, v76, v75
	v_cvt_f32_i32_e32 v75, v75
	v_rcp_iflag_f32_e32 v75, v75
	v_add_f32_e32 v77, 0, v49
	v_add_f32_e32 v77, v77, v50
	v_fma_f32 v77, v75, v77, -v50
	ds_write_b32 v72, v77 offset:21024
	v_add_u32_e32 v74, 3, v73
	v_subrev_u32_e32 v75, s6, v74
	v_add_u32_e32 v76, s6, v74
	v_max_i32_e32 v75, 0, v75
	v_min_i32_e32 v76, 0x2000, v76
	v_sub_u32_e32 v75, v76, v75
	v_cvt_f32_i32_e32 v75, v75
	v_rcp_iflag_f32_e32 v75, v75
	v_add_f32_e32 v77, 0, v50
	v_add_f32_e32 v77, v77, v51
	v_fma_f32 v77, v75, v77, -v51
	ds_write_b32 v72, v77 offset:21296
	v_add_u32_e32 v74, 4, v73
	v_subrev_u32_e32 v75, s6, v74
	v_add_u32_e32 v76, s6, v74
	v_max_i32_e32 v75, 0, v75
	v_min_i32_e32 v76, 0x2000, v76
	v_sub_u32_e32 v75, v76, v75
	v_cvt_f32_i32_e32 v75, v75
	v_rcp_iflag_f32_e32 v75, v75
	v_add_f32_e32 v77, 0, v51
	v_add_f32_e32 v77, v77, v52
	v_fma_f32 v77, v75, v77, -v52
	ds_write_b32 v72, v77 offset:21568
	v_add_u32_e32 v74, 5, v73
	v_subrev_u32_e32 v75, s6, v74
	v_add_u32_e32 v76, s6, v74
	v_max_i32_e32 v75, 0, v75
	v_min_i32_e32 v76, 0x2000, v76
	v_sub_u32_e32 v75, v76, v75
	v_cvt_f32_i32_e32 v75, v75
	v_rcp_iflag_f32_e32 v75, v75
	v_add_f32_e32 v77, 0, v52
	v_add_f32_e32 v77, v77, v53
	v_fma_f32 v77, v75, v77, -v53
	ds_write_b32 v72, v77 offset:21840
	v_add_u32_e32 v74, 6, v73
	v_subrev_u32_e32 v75, s6, v74
	v_add_u32_e32 v76, s6, v74
	v_max_i32_e32 v75, 0, v75
	v_min_i32_e32 v76, 0x2000, v76
	v_sub_u32_e32 v75, v76, v75
	v_cvt_f32_i32_e32 v75, v75
	v_rcp_iflag_f32_e32 v75, v75
	v_add_f32_e32 v77, 0, v53
	v_add_f32_e32 v77, v77, v54
	v_fma_f32 v77, v75, v77, -v54
	ds_write_b32 v72, v77 offset:22112
	v_add_u32_e32 v74, 7, v73
	v_subrev_u32_e32 v75, s6, v74
	v_add_u32_e32 v76, s6, v74
	v_max_i32_e32 v75, 0, v75
	v_min_i32_e32 v76, 0x2000, v76
	v_sub_u32_e32 v75, v76, v75
	v_cvt_f32_i32_e32 v75, v75
	v_rcp_iflag_f32_e32 v75, v75
	v_add_f32_e32 v77, 0, v54
	v_add_f32_e32 v77, v77, v55
	v_fma_f32 v77, v75, v77, -v55
	ds_write_b32 v72, v77 offset:22384
	v_add_u32_e32 v74, 8, v73
	v_subrev_u32_e32 v75, s6, v74
	v_add_u32_e32 v76, s6, v74
	v_max_i32_e32 v75, 0, v75
	v_min_i32_e32 v76, 0x2000, v76
	v_sub_u32_e32 v75, v76, v75
	v_cvt_f32_i32_e32 v75, v75
	v_rcp_iflag_f32_e32 v75, v75
	v_add_f32_e32 v77, 0, v55
	v_add_f32_e32 v77, v77, v56
	v_fma_f32 v77, v75, v77, -v56
	ds_write_b32 v72, v77 offset:22656
	v_add_u32_e32 v74, 9, v73
	v_subrev_u32_e32 v75, s6, v74
	v_add_u32_e32 v76, s6, v74
	v_max_i32_e32 v75, 0, v75
	v_min_i32_e32 v76, 0x2000, v76
	v_sub_u32_e32 v75, v76, v75
	v_cvt_f32_i32_e32 v75, v75
	v_rcp_iflag_f32_e32 v75, v75
	v_add_f32_e32 v77, 0, v56
	v_add_f32_e32 v77, v77, v57
	v_fma_f32 v77, v75, v77, -v57
	ds_write_b32 v72, v77 offset:22928
	v_add_u32_e32 v74, 10, v73
	v_subrev_u32_e32 v75, s6, v74
; DI void pool_item(const Params& p, int layer, int seq, int tile, int g, char* smem) {
;     ...
;     const int e = tid & 63, tq = tid >> 6;
; #pragma unroll 4
;     for (int i = 0; i < 16; ++i) {
;         const int tt = tq * 16 + i, t = t0 + tt;
;         const int lo = t - w2 < 0 ? 0 : t - w2, hi = t + w2 > Ls ? Ls : t + w2;
;         float s = 0.f;
;         for (int q = lo; q < hi; ++q) s += su[(q - t0 + 8) * 64 + e];
;         sd[tt * 68 + e] = s * __builtin_amdgcn_rcpf((float)(hi - lo)) - su[(tt + 8) * 64 + e];
;     }
	v_add_u32_e32 v76, s6, v74
	v_max_i32_e32 v75, 0, v75
	v_min_i32_e32 v76, 0x2000, v76
	v_sub_u32_e32 v75, v76, v75
	v_cvt_f32_i32_e32 v75, v75
	v_rcp_iflag_f32_e32 v75, v75
	v_add_f32_e32 v77, 0, v57
	v_add_f32_e32 v77, v77, v58
	v_fma_f32 v77, v75, v77, -v58
	ds_write_b32 v72, v77 offset:23200
	v_add_u32_e32 v74, 11, v73
	v_subrev_u32_e32 v75, s6, v74
	v_add_u32_e32 v76, s6, v74
	v_max_i32_e32 v75, 0, v75
	v_min_i32_e32 v76, 0x2000, v76
	v_sub_u32_e32 v75, v76, v75
	v_cvt_f32_i32_e32 v75, v75
	v_rcp_iflag_f32_e32 v75, v75
	v_add_f32_e32 v77, 0, v58
	v_add_f32_e32 v77, v77, v59
	v_fma_f32 v77, v75, v77, -v59
	ds_write_b32 v72, v77 offset:23472
	v_add_u32_e32 v74, 12, v73
	v_subrev_u32_e32 v75, s6, v74
	v_add_u32_e32 v76, s6, v74
	v_max_i32_e32 v75, 0, v75
	v_min_i32_e32 v76, 0x2000, v76
	v_sub_u32_e32 v75, v76, v75
	v_cvt_f32_i32_e32 v75, v75
	v_rcp_iflag_f32_e32 v75, v75
	v_add_f32_e32 v77, 0, v59
	v_add_f32_e32 v77, v77, v60
	v_fma_f32 v77, v75, v77, -v60
	ds_write_b32 v72, v77 offset:23744
	v_add_u32_e32 v74, 13, v73
	v_subrev_u32_e32 v75, s6, v74
	v_add_u32_e32 v76, s6, v74
	v_max_i32_e32 v75, 0, v75
	v_min_i32_e32 v76, 0x2000, v76
	v_sub_u32_e32 v75, v76, v75
	v_cvt_f32_i32_e32 v75, v75
	v_rcp_iflag_f32_e32 v75, v75
	v_add_f32_e32 v77, 0, v60
	v_add_f32_e32 v77, v77, v61
	v_fma_f32 v77, v75, v77, -v61
	ds_write_b32 v72, v77 offset:24016
	v_add_u32_e32 v74, 14, v73
	v_subrev_u32_e32 v75, s6, v74
	v_add_u32_e32 v76, s6, v74
	v_max_i32_e32 v75, 0, v75
	v_min_i32_e32 v76, 0x2000, v76
	v_sub_u32_e32 v75, v76, v75
	v_cvt_f32_i32_e32 v75, v75
	v_rcp_iflag_f32_e32 v75, v75
	v_add_f32_e32 v77, 0, v61
	v_add_f32_e32 v77, v77, v62
	v_fma_f32 v77, v75, v77, -v62
	ds_write_b32 v72, v77 offset:24288
	v_add_u32_e32 v74, 15, v73
	v_subrev_u32_e32 v75, s6, v74
	v_add_u32_e32 v76, s6, v74
	v_max_i32_e32 v75, 0, v75
	v_min_i32_e32 v76, 0x2000, v76
	v_sub_u32_e32 v75, v76, v75
	v_cvt_f32_i32_e32 v75, v75
	v_rcp_iflag_f32_e32 v75, v75
	v_add_f32_e32 v77, 0, v62
	v_add_f32_e32 v77, v77, v63
	v_fma_f32 v77, v75, v77, -v63
	ds_write_b32 v72, v77 offset:24560
	s_branch .LBB0_304
.Lrelay_604:
	s_branch .LBB0_604
.Lrelay_605:
	s_branch .LBB0_605
.Lpw_g1:
	v_lshl_add_u32 v71, v2, 8, v0
	ds_read_b32 v46, v71 offset:1536
	ds_read_b32 v47, v71 offset:1792
	ds_read_b32 v48, v71 offset:2048
	ds_read_b32 v49, v71 offset:2304
	ds_read_b32 v50, v71 offset:2560
	ds_read_b32 v51, v71 offset:2816
	ds_read_b32 v52, v71 offset:3072
	ds_read_b32 v53, v71 offset:3328
	ds_read_b32 v54, v71 offset:3584
	ds_read_b32 v55, v71 offset:3840
	ds_read_b32 v56, v71 offset:4096
	ds_read_b32 v57, v71 offset:4352
	ds_read_b32 v58, v71 offset:4608
	ds_read_b32 v59, v71 offset:4864
	ds_read_b32 v60, v71 offset:5120
	ds_read_b32 v61, v71 offset:5376
	ds_read_b32 v62, v71 offset:5632
	ds_read_b32 v63, v71 offset:5888
	ds_read_b32 v64, v71 offset:6144
	v_mad_u32_u24 v72, v2, s30, v0
	v_add_u32_e32 v73, s26, v2
	s_waitcnt lgkmcnt(0)
	v_subrev_u32_e32 v75, s6, v73
	v_add_u32_e32 v76, s6, v73
	v_max_i32_e32 v75, 0, v75
	v_min_i32_e32 v76, 0x2000, v76
	v_sub_u32_e32 v75, v76, v75
	v_cvt_f32_i32_e32 v75, v75
	v_rcp_iflag_f32_e32 v75, v75
	v_add_f32_e32 v77, 0, v46
	v_add_f32_e32 v77, v77, v47
	v_add_f32_e32 v77, v77, v48
	v_add_f32_e32 v77, v77, v49
	v_fma_f32 v77, v75, v77, -v48
	ds_write_b32 v72, v77 offset:20480
	v_add_u32_e32 v74, 1, v73
	v_subrev_u32_e32 v75, s6, v74
	v_add_u32_e32 v76, s6, v74
	v_max_i32_e32 v75, 0, v75
	v_min_i32_e32 v76, 0x2000, v76
	v_sub_u32_e32 v75, v76, v75
	v_cvt_f32_i32_e32 v75, v75
	v_rcp_iflag_f32_e32 v75, v75
	v_add_f32_e32 v77, 0, v47
	v_add_f32_e32 v77, v77, v48
	v_add_f32_e32 v77, v77, v49
	v_add_f32_e32 v77, v77, v50
	v_fma_f32 v77, v75, v77, -v49
	ds_write_b32 v72, v77 offset:20752
	v_add_u32_e32 v74, 2, v73
	v_subrev_u32_e32 v75, s6, v74
	v_add_u32_e32 v76, s6, v74
	v_max_i32_e32 v75, 0, v75
	v_min_i32_e32 v76, 0x2000, v76
	v_sub_u32_e32 v75, v76, v75
	v_cvt_f32_i32_e32 v75, v75
	v_rcp_iflag_f32_e32 v75, v75
	v_add_f32_e32 v77, 0, v48
	v_add_f32_e32 v77, v77, v49
	v_add_f32_e32 v77, v77, v50
	v_add_f32_e32 v77, v77, v51
	v_fma_f32 v77, v75, v77, -v50
	ds_write_b32 v72, v77 offset:21024
	v_add_u32_e32 v74, 3, v73
	v_subrev_u32_e32 v75, s6, v74
	v_add_u32_e32 v76, s6, v74
	v_max_i32_e32 v75, 0, v75
	v_min_i32_e32 v76, 0x2000, v76
	v_sub_u32_e32 v75, v76, v75
	v_cvt_f32_i32_e32 v75, v75
	v_rcp_iflag_f32_e32 v75, v75
	v_add_f32_e32 v77, 0, v49
	v_add_f32_e32 v77, v77, v50
	v_add_f32_e32 v77, v77, v51
	v_add_f32_e32 v77, v77, v52
	v_fma_f32 v77, v75, v77, -v51
	ds_write_b32 v72, v77 offset:21296
	v_add_u32_e32 v74, 4, v73
	v_subrev_u32_e32 v75, s6, v74
	v_add_u32_e32 v76, s6, v74
	v_max_i32_e32 v75, 0, v75
	v_min_i32_e32 v76, 0x2000, v76
	v_sub_u32_e32 v75, v76, v75
	v_cvt_f32_i32_e32 v75, v75
	v_rcp_iflag_f32_e32 v75, v75
	v_add_f32_e32 v77, 0, v50
	v_add_f32_e32 v77, v77, v51
	v_add_f32_e32 v77, v77, v52
	v_add_f32_e32 v77, v77, v53
	v_fma_f32 v77, v75, v77, -v52
	ds_write_b32 v72, v77 offset:21568
	v_add_u32_e32 v74, 5, v73
	v_subrev_u32_e32 v75, s6, v74
	v_add_u32_e32 v76, s6, v74
	v_max_i32_e32 v75, 0, v75
	v_min_i32_e32 v76, 0x2000, v76
	v_sub_u32_e32 v75, v76, v75
	v_cvt_f32_i32_e32 v75, v75
	v_rcp_iflag_f32_e32 v75, v75
	v_add_f32_e32 v77, 0, v51
	v_add_f32_e32 v77, v77, v52
	v_add_f32_e32 v77, v77, v53
	v_add_f32_e32 v77, v77, v54
	v_fma_f32 v77, v75, v77, -v53
	ds_write_b32 v72, v77 offset:21840
	v_add_u32_e32 v74, 6, v73
	v_subrev_u32_e32 v75, s6, v74
	v_add_u32_e32 v76, s6, v74
	v_max_i32_e32 v75, 0, v75
	v_min_i32_e32 v76, 0x2000, v76
	v_sub_u32_e32 v75, v76, v75
	v_cvt_f32_i32_e32 v75, v75
	v_rcp_iflag_f32_e32 v75, v75
	v_add_f32_e32 v77, 0, v52
; DI void pool_item(const Params& p, int layer, int seq, int tile, int g, char* smem) {
;     ...
;     const int e = tid & 63, tq = tid >> 6;
; #pragma unroll 4
;     for (int i = 0; i < 16; ++i) {
;         const int tt = tq * 16 + i, t = t0 + tt;
;         const int lo = t - w2 < 0 ? 0 : t - w2, hi = t + w2 > Ls ? Ls : t + w2;
;         float s = 0.f;
;         for (int q = lo; q < hi; ++q) s += su[(q - t0 + 8) * 64 + e];
;         sd[tt * 68 + e] = s * __builtin_amdgcn_rcpf((float)(hi - lo)) - su[(tt + 8) * 64 + e];
;     }
	v_add_f32_e32 v77, v77, v53
	v_add_f32_e32 v77, v77, v54
	v_add_f32_e32 v77, v77, v55
	v_fma_f32 v77, v75, v77, -v54
	ds_write_b32 v72, v77 offset:22112
	v_add_u32_e32 v74, 7, v73
	v_subrev_u32_e32 v75, s6, v74
	v_add_u32_e32 v76, s6, v74
	v_max_i32_e32 v75, 0, v75
	v_min_i32_e32 v76, 0x2000, v76
	v_sub_u32_e32 v75, v76, v75
	v_cvt_f32_i32_e32 v75, v75
	v_rcp_iflag_f32_e32 v75, v75
	v_add_f32_e32 v77, 0, v53
	v_add_f32_e32 v77, v77, v54
	v_add_f32_e32 v77, v77, v55
	v_add_f32_e32 v77, v77, v56
	v_fma_f32 v77, v75, v77, -v55
	ds_write_b32 v72, v77 offset:22384
	v_add_u32_e32 v74, 8, v73
	v_subrev_u32_e32 v75, s6, v74
	v_add_u32_e32 v76, s6, v74
	v_max_i32_e32 v75, 0, v75
	v_min_i32_e32 v76, 0x2000, v76
	v_sub_u32_e32 v75, v76, v75
	v_cvt_f32_i32_e32 v75, v75
	v_rcp_iflag_f32_e32 v75, v75
	v_add_f32_e32 v77, 0, v54
	v_add_f32_e32 v77, v77, v55
	v_add_f32_e32 v77, v77, v56
	v_add_f32_e32 v77, v77, v57
	v_fma_f32 v77, v75, v77, -v56
	ds_write_b32 v72, v77 offset:22656
	v_add_u32_e32 v74, 9, v73
	v_subrev_u32_e32 v75, s6, v74
	v_add_u32_e32 v76, s6, v74
	v_max_i32_e32 v75, 0, v75
	v_min_i32_e32 v76, 0x2000, v76
	v_sub_u32_e32 v75, v76, v75
	v_cvt_f32_i32_e32 v75, v75
	v_rcp_iflag_f32_e32 v75, v75
	v_add_f32_e32 v77, 0, v55
	v_add_f32_e32 v77, v77, v56
	v_add_f32_e32 v77, v77, v57
	v_add_f32_e32 v77, v77, v58
	v_fma_f32 v77, v75, v77, -v57
	ds_write_b32 v72, v77 offset:22928
	v_add_u32_e32 v74, 10, v73
	v_subrev_u32_e32 v75, s6, v74
	v_add_u32_e32 v76, s6, v74
	v_max_i32_e32 v75, 0, v75
	v_min_i32_e32 v76, 0x2000, v76
	v_sub_u32_e32 v75, v76, v75
	v_cvt_f32_i32_e32 v75, v75
	v_rcp_iflag_f32_e32 v75, v75
	v_add_f32_e32 v77, 0, v56
	v_add_f32_e32 v77, v77, v57
	v_add_f32_e32 v77, v77, v58
	v_add_f32_e32 v77, v77, v59
	v_fma_f32 v77, v75, v77, -v58
	ds_write_b32 v72, v77 offset:23200
	v_add_u32_e32 v74, 11, v73
	v_subrev_u32_e32 v75, s6, v74
	v_add_u32_e32 v76, s6, v74
	v_max_i32_e32 v75, 0, v75
	v_min_i32_e32 v76, 0x2000, v76
	v_sub_u32_e32 v75, v76, v75
	v_cvt_f32_i32_e32 v75, v75
	v_rcp_iflag_f32_e32 v75, v75
	v_add_f32_e32 v77, 0, v57
	v_add_f32_e32 v77, v77, v58
	v_add_f32_e32 v77, v77, v59
	v_add_f32_e32 v77, v77, v60
	v_fma_f32 v77, v75, v77, -v59
	ds_write_b32 v72, v77 offset:23472
	v_add_u32_e32 v74, 12, v73
	v_subrev_u32_e32 v75, s6, v74
	v_add_u32_e32 v76, s6, v74
	v_max_i32_e32 v75, 0, v75
	v_min_i32_e32 v76, 0x2000, v76
	v_sub_u32_e32 v75, v76, v75
	v_cvt_f32_i32_e32 v75, v75
	v_rcp_iflag_f32_e32 v75, v75
	v_add_f32_e32 v77, 0, v58
	v_add_f32_e32 v77, v77, v59
	v_add_f32_e32 v77, v77, v60
	v_add_f32_e32 v77, v77, v61
	v_fma_f32 v77, v75, v77, -v60
	ds_write_b32 v72, v77 offset:23744
	v_add_u32_e32 v74, 13, v73
	v_subrev_u32_e32 v75, s6, v74
	v_add_u32_e32 v76, s6, v74
	v_max_i32_e32 v75, 0, v75
	v_min_i32_e32 v76, 0x2000, v76
	v_sub_u32_e32 v75, v76, v75
	v_cvt_f32_i32_e32 v75, v75
	v_rcp_iflag_f32_e32 v75, v75
	v_add_f32_e32 v77, 0, v59
	v_add_f32_e32 v77, v77, v60
	v_add_f32_e32 v77, v77, v61
	v_add_f32_e32 v77, v77, v62
	v_fma_f32 v77, v75, v77, -v61
	ds_write_b32 v72, v77 offset:24016
	v_add_u32_e32 v74, 14, v73
	v_subrev_u32_e32 v75, s6, v74
	v_add_u32_e32 v76, s6, v74
	v_max_i32_e32 v75, 0, v75
	v_min_i32_e32 v76, 0x2000, v76
	v_sub_u32_e32 v75, v76, v75
	v_cvt_f32_i32_e32 v75, v75
	v_rcp_iflag_f32_e32 v75, v75
	v_add_f32_e32 v77, 0, v60
	v_add_f32_e32 v77, v77, v61
	v_add_f32_e32 v77, v77, v62
	v_add_f32_e32 v77, v77, v63
	v_fma_f32 v77, v75, v77, -v62
	ds_write_b32 v72, v77 offset:24288
	v_add_u32_e32 v74, 15, v73
	v_subrev_u32_e32 v75, s6, v74
	v_add_u32_e32 v76, s6, v74
	v_max_i32_e32 v75, 0, v75
	v_min_i32_e32 v76, 0x2000, v76
	v_sub_u32_e32 v75, v76, v75
	v_cvt_f32_i32_e32 v75, v75
	v_rcp_iflag_f32_e32 v75, v75
	v_add_f32_e32 v77, 0, v61
	v_add_f32_e32 v77, v77, v62
	v_add_f32_e32 v77, v77, v63
	v_add_f32_e32 v77, v77, v64
	v_fma_f32 v77, v75, v77, -v63
	ds_write_b32 v72, v77 offset:24560
	s_branch .LBB0_304
.Lpw_g2:
	v_lshl_add_u32 v71, v2, 8, v0
	ds_read_b32 v44, v71 offset:1024
	ds_read_b32 v45, v71 offset:1280
	ds_read_b32 v46, v71 offset:1536
	ds_read_b32 v47, v71 offset:1792
	ds_read_b32 v48, v71 offset:2048
	ds_read_b32 v49, v71 offset:2304
	ds_read_b32 v50, v71 offset:2560
	ds_read_b32 v51, v71 offset:2816
	ds_read_b32 v52, v71 offset:3072
	ds_read_b32 v53, v71 offset:3328
	ds_read_b32 v54, v71 offset:3584
	ds_read_b32 v55, v71 offset:3840
	ds_read_b32 v56, v71 offset:4096
	ds_read_b32 v57, v71 offset:4352
	ds_read_b32 v58, v71 offset:4608
	ds_read_b32 v59, v71 offset:4864
	ds_read_b32 v60, v71 offset:5120
	ds_read_b32 v61, v71 offset:5376
	ds_read_b32 v62, v71 offset:5632
	ds_read_b32 v63, v71 offset:5888
	ds_read_b32 v64, v71 offset:6144
	ds_read_b32 v65, v71 offset:6400
	ds_read_b32 v66, v71 offset:6656
	v_mad_u32_u24 v72, v2, s30, v0
	v_add_u32_e32 v73, s26, v2
	s_waitcnt lgkmcnt(0)
; DI void pool_item(const Params& p, int layer, int seq, int tile, int g, char* smem) {
;     ...
;     const int e = tid & 63, tq = tid >> 6;
; #pragma unroll 4
;     for (int i = 0; i < 16; ++i) {
;         const int tt = tq * 16 + i, t = t0 + tt;
;         const int lo = t - w2 < 0 ? 0 : t - w2, hi = t + w2 > Ls ? Ls : t + w2;
;         float s = 0.f;
;         for (int q = lo; q < hi; ++q) s += su[(q - t0 + 8) * 64 + e];
;         sd[tt * 68 + e] = s * __builtin_amdgcn_rcpf((float)(hi - lo)) - su[(tt + 8) * 64 + e];
;     }
	v_subrev_u32_e32 v75, s6, v73
	v_add_u32_e32 v76, s6, v73
	v_max_i32_e32 v75, 0, v75
	v_min_i32_e32 v76, 0x2000, v76
	v_sub_u32_e32 v75, v76, v75
	v_cvt_f32_i32_e32 v75, v75
	v_rcp_iflag_f32_e32 v75, v75
	v_add_f32_e32 v77, 0, v44
	v_add_f32_e32 v77, v77, v45
	v_add_f32_e32 v77, v77, v46
	v_add_f32_e32 v77, v77, v47
	v_add_f32_e32 v77, v77, v48
	v_add_f32_e32 v77, v77, v49
	v_add_f32_e32 v77, v77, v50
	v_add_f32_e32 v77, v77, v51
	v_fma_f32 v77, v75, v77, -v48
	ds_write_b32 v72, v77 offset:20480
	v_add_u32_e32 v74, 1, v73
	v_subrev_u32_e32 v75, s6, v74
	v_add_u32_e32 v76, s6, v74
	v_max_i32_e32 v75, 0, v75
	v_min_i32_e32 v76, 0x2000, v76
	v_sub_u32_e32 v75, v76, v75
	v_cvt_f32_i32_e32 v75, v75
	v_rcp_iflag_f32_e32 v75, v75
	v_add_f32_e32 v77, 0, v45
	v_add_f32_e32 v77, v77, v46
	v_add_f32_e32 v77, v77, v47
	v_add_f32_e32 v77, v77, v48
	v_add_f32_e32 v77, v77, v49
	v_add_f32_e32 v77, v77, v50
	v_add_f32_e32 v77, v77, v51
	v_add_f32_e32 v77, v77, v52
	v_fma_f32 v77, v75, v77, -v49
	ds_write_b32 v72, v77 offset:20752
	v_add_u32_e32 v74, 2, v73
	v_subrev_u32_e32 v75, s6, v74
	v_add_u32_e32 v76, s6, v74
	v_max_i32_e32 v75, 0, v75
	v_min_i32_e32 v76, 0x2000, v76
	v_sub_u32_e32 v75, v76, v75
	v_cvt_f32_i32_e32 v75, v75
	v_rcp_iflag_f32_e32 v75, v75
	v_add_f32_e32 v77, 0, v46
	v_add_f32_e32 v77, v77, v47
	v_add_f32_e32 v77, v77, v48
	v_add_f32_e32 v77, v77, v49
	v_add_f32_e32 v77, v77, v50
	v_add_f32_e32 v77, v77, v51
	v_add_f32_e32 v77, v77, v52
	v_add_f32_e32 v77, v77, v53
	v_fma_f32 v77, v75, v77, -v50
	ds_write_b32 v72, v77 offset:21024
	v_add_u32_e32 v74, 3, v73
	v_subrev_u32_e32 v75, s6, v74
	v_add_u32_e32 v76, s6, v74
	v_max_i32_e32 v75, 0, v75
	v_min_i32_e32 v76, 0x2000, v76
	v_sub_u32_e32 v75, v76, v75
	v_cvt_f32_i32_e32 v75, v75
	v_rcp_iflag_f32_e32 v75, v75
	v_add_f32_e32 v77, 0, v47
	v_add_f32_e32 v77, v77, v48
	v_add_f32_e32 v77, v77, v49
	v_add_f32_e32 v77, v77, v50
	v_add_f32_e32 v77, v77, v51
	v_add_f32_e32 v77, v77, v52
	v_add_f32_e32 v77, v77, v53
	v_add_f32_e32 v77, v77, v54
	v_fma_f32 v77, v75, v77, -v51
	ds_write_b32 v72, v77 offset:21296
	v_add_u32_e32 v74, 4, v73
	v_subrev_u32_e32 v75, s6, v74
	v_add_u32_e32 v76, s6, v74
	v_max_i32_e32 v75, 0, v75
	v_min_i32_e32 v76, 0x2000, v76
	v_sub_u32_e32 v75, v76, v75
	v_cvt_f32_i32_e32 v75, v75
	v_rcp_iflag_f32_e32 v75, v75
	v_add_f32_e32 v77, 0, v48
	v_add_f32_e32 v77, v77, v49
	v_add_f32_e32 v77, v77, v50
	v_add_f32_e32 v77, v77, v51
	v_add_f32_e32 v77, v77, v52
	v_add_f32_e32 v77, v77, v53
	v_add_f32_e32 v77, v77, v54
	v_add_f32_e32 v77, v77, v55
	v_fma_f32 v77, v75, v77, -v52
	ds_write_b32 v72, v77 offset:21568
	v_add_u32_e32 v74, 5, v73
	v_subrev_u32_e32 v75, s6, v74
	v_add_u32_e32 v76, s6, v74
	v_max_i32_e32 v75, 0, v75
	v_min_i32_e32 v76, 0x2000, v76
	v_sub_u32_e32 v75, v76, v75
	v_cvt_f32_i32_e32 v75, v75
	v_rcp_iflag_f32_e32 v75, v75
	v_add_f32_e32 v77, 0, v49
	v_add_f32_e32 v77, v77, v50
	v_add_f32_e32 v77, v77, v51
	v_add_f32_e32 v77, v77, v52
	v_add_f32_e32 v77, v77, v53
	v_add_f32_e32 v77, v77, v54
	v_add_f32_e32 v77, v77, v55
	v_add_f32_e32 v77, v77, v56
	v_fma_f32 v77, v75, v77, -v53
	ds_write_b32 v72, v77 offset:21840
	v_add_u32_e32 v74, 6, v73
	v_subrev_u32_e32 v75, s6, v74
	v_add_u32_e32 v76, s6, v74
	v_max_i32_e32 v75, 0, v75
	v_min_i32_e32 v76, 0x2000, v76
	v_sub_u32_e32 v75, v76, v75
	v_cvt_f32_i32_e32 v75, v75
	v_rcp_iflag_f32_e32 v75, v75
	v_add_f32_e32 v77, 0, v50
	v_add_f32_e32 v77, v77, v51
	v_add_f32_e32 v77, v77, v52
	v_add_f32_e32 v77, v77, v53
	v_add_f32_e32 v77, v77, v54
	v_add_f32_e32 v77, v77, v55
	v_add_f32_e32 v77, v77, v56
	v_add_f32_e32 v77, v77, v57
	v_fma_f32 v77, v75, v77, -v54
	ds_write_b32 v72, v77 offset:22112
	v_add_u32_e32 v74, 7, v73
	v_subrev_u32_e32 v75, s6, v74
	v_add_u32_e32 v76, s6, v74
	v_max_i32_e32 v75, 0, v75
	v_min_i32_e32 v76, 0x2000, v76
	v_sub_u32_e32 v75, v76, v75
	v_cvt_f32_i32_e32 v75, v75
	v_rcp_iflag_f32_e32 v75, v75
	v_add_f32_e32 v77, 0, v51
	v_add_f32_e32 v77, v77, v52
	v_add_f32_e32 v77, v77, v53
	v_add_f32_e32 v77, v77, v54
	v_add_f32_e32 v77, v77, v55
	v_add_f32_e32 v77, v77, v56
	v_add_f32_e32 v77, v77, v57
	v_add_f32_e32 v77, v77, v58
	v_fma_f32 v77, v75, v77, -v55
	ds_write_b32 v72, v77 offset:22384
	v_add_u32_e32 v74, 8, v73
	v_subrev_u32_e32 v75, s6, v74
	v_add_u32_e32 v76, s6, v74
	v_max_i32_e32 v75, 0, v75
	v_min_i32_e32 v76, 0x2000, v76
	v_sub_u32_e32 v75, v76, v75
	v_cvt_f32_i32_e32 v75, v75
	v_rcp_iflag_f32_e32 v75, v75
	v_add_f32_e32 v77, 0, v52
	v_add_f32_e32 v77, v77, v53
	v_add_f32_e32 v77, v77, v54
	v_add_f32_e32 v77, v77, v55
	v_add_f32_e32 v77, v77, v56
	v_add_f32_e32 v77, v77, v57
	v_add_f32_e32 v77, v77, v58
	v_add_f32_e32 v77, v77, v59
	v_fma_f32 v77, v75, v77, -v56
	ds_write_b32 v72, v77 offset:22656
	v_add_u32_e32 v74, 9, v73
	v_subrev_u32_e32 v75, s6, v74
	v_add_u32_e32 v76, s6, v74
	v_max_i32_e32 v75, 0, v75
	v_min_i32_e32 v76, 0x2000, v76
	v_sub_u32_e32 v75, v76, v75
	v_cvt_f32_i32_e32 v75, v75
	v_rcp_iflag_f32_e32 v75, v75
	v_add_f32_e32 v77, 0, v53
	v_add_f32_e32 v77, v77, v54
	v_add_f32_e32 v77, v77, v55
	v_add_f32_e32 v77, v77, v56
	v_add_f32_e32 v77, v77, v57
	v_add_f32_e32 v77, v77, v58
	v_add_f32_e32 v77, v77, v59
	v_add_f32_e32 v77, v77, v60
	v_fma_f32 v77, v75, v77, -v57
	ds_write_b32 v72, v77 offset:22928
	v_add_u32_e32 v74, 10, v73
	v_subrev_u32_e32 v75, s6, v74
	v_add_u32_e32 v76, s6, v74
	v_max_i32_e32 v75, 0, v75
	v_min_i32_e32 v76, 0x2000, v76
	v_sub_u32_e32 v75, v76, v75
	v_cvt_f32_i32_e32 v75, v75
	v_rcp_iflag_f32_e32 v75, v75
	v_add_f32_e32 v77, 0, v54
	v_add_f32_e32 v77, v77, v55
	v_add_f32_e32 v77, v77, v56
	v_add_f32_e32 v77, v77, v57
	v_add_f32_e32 v77, v77, v58
; DI void pool_item(const Params& p, int layer, int seq, int tile, int g, char* smem) {
;     ...
;     const int e = tid & 63, tq = tid >> 6;
; #pragma unroll 4
;     for (int i = 0; i < 16; ++i) {
;         const int tt = tq * 16 + i, t = t0 + tt;
;         const int lo = t - w2 < 0 ? 0 : t - w2, hi = t + w2 > Ls ? Ls : t + w2;
;         float s = 0.f;
;         for (int q = lo; q < hi; ++q) s += su[(q - t0 + 8) * 64 + e];
;         sd[tt * 68 + e] = s * __builtin_amdgcn_rcpf((float)(hi - lo)) - su[(tt + 8) * 64 + e];
;     }
	v_add_f32_e32 v77, v77, v59
	v_add_f32_e32 v77, v77, v60
	v_add_f32_e32 v77, v77, v61
	v_fma_f32 v77, v75, v77, -v58
	ds_write_b32 v72, v77 offset:23200
	v_add_u32_e32 v74, 11, v73
	v_subrev_u32_e32 v75, s6, v74
	v_add_u32_e32 v76, s6, v74
	v_max_i32_e32 v75, 0, v75
	v_min_i32_e32 v76, 0x2000, v76
	v_sub_u32_e32 v75, v76, v75
	v_cvt_f32_i32_e32 v75, v75
	v_rcp_iflag_f32_e32 v75, v75
	v_add_f32_e32 v77, 0, v55
	v_add_f32_e32 v77, v77, v56
	v_add_f32_e32 v77, v77, v57
	v_add_f32_e32 v77, v77, v58
	v_add_f32_e32 v77, v77, v59
	v_add_f32_e32 v77, v77, v60
	v_add_f32_e32 v77, v77, v61
	v_add_f32_e32 v77, v77, v62
	v_fma_f32 v77, v75, v77, -v59
	ds_write_b32 v72, v77 offset:23472
	v_add_u32_e32 v74, 12, v73
	v_subrev_u32_e32 v75, s6, v74
	v_add_u32_e32 v76, s6, v74
	v_max_i32_e32 v75, 0, v75
	v_min_i32_e32 v76, 0x2000, v76
	v_sub_u32_e32 v75, v76, v75
	v_cvt_f32_i32_e32 v75, v75
	v_rcp_iflag_f32_e32 v75, v75
	v_add_f32_e32 v77, 0, v56
	v_add_f32_e32 v77, v77, v57
	v_add_f32_e32 v77, v77, v58
	v_add_f32_e32 v77, v77, v59
	v_add_f32_e32 v77, v77, v60
	v_add_f32_e32 v77, v77, v61
	v_add_f32_e32 v77, v77, v62
	v_add_f32_e32 v77, v77, v63
	v_fma_f32 v77, v75, v77, -v60
	ds_write_b32 v72, v77 offset:23744
	v_add_u32_e32 v74, 13, v73
	v_subrev_u32_e32 v75, s6, v74
	v_add_u32_e32 v76, s6, v74
	v_max_i32_e32 v75, 0, v75
	v_min_i32_e32 v76, 0x2000, v76
	v_sub_u32_e32 v75, v76, v75
	v_cvt_f32_i32_e32 v75, v75
	v_rcp_iflag_f32_e32 v75, v75
	v_add_f32_e32 v77, 0, v57
	v_add_f32_e32 v77, v77, v58
	v_add_f32_e32 v77, v77, v59
	v_add_f32_e32 v77, v77, v60
	v_add_f32_e32 v77, v77, v61
	v_add_f32_e32 v77, v77, v62
	v_add_f32_e32 v77, v77, v63
	v_add_f32_e32 v77, v77, v64
	v_fma_f32 v77, v75, v77, -v61
	ds_write_b32 v72, v77 offset:24016
	v_add_u32_e32 v74, 14, v73
	v_subrev_u32_e32 v75, s6, v74
	v_add_u32_e32 v76, s6, v74
	v_max_i32_e32 v75, 0, v75
	v_min_i32_e32 v76, 0x2000, v76
	v_sub_u32_e32 v75, v76, v75
	v_cvt_f32_i32_e32 v75, v75
	v_rcp_iflag_f32_e32 v75, v75
	v_add_f32_e32 v77, 0, v58
	v_add_f32_e32 v77, v77, v59
	v_add_f32_e32 v77, v77, v60
	v_add_f32_e32 v77, v77, v61
	v_add_f32_e32 v77, v77, v62
	v_add_f32_e32 v77, v77, v63
	v_add_f32_e32 v77, v77, v64
	v_add_f32_e32 v77, v77, v65
	v_fma_f32 v77, v75, v77, -v62
	ds_write_b32 v72, v77 offset:24288
	v_add_u32_e32 v74, 15, v73
	v_subrev_u32_e32 v75, s6, v74
	v_add_u32_e32 v76, s6, v74
	v_max_i32_e32 v75, 0, v75
	v_min_i32_e32 v76, 0x2000, v76
	v_sub_u32_e32 v75, v76, v75
	v_cvt_f32_i32_e32 v75, v75
	v_rcp_iflag_f32_e32 v75, v75
	v_add_f32_e32 v77, 0, v59
	v_add_f32_e32 v77, v77, v60
	v_add_f32_e32 v77, v77, v61
	v_add_f32_e32 v77, v77, v62
	v_add_f32_e32 v77, v77, v63
	v_add_f32_e32 v77, v77, v64
	v_add_f32_e32 v77, v77, v65
	v_add_f32_e32 v77, v77, v66
	v_fma_f32 v77, v75, v77, -v63
	ds_write_b32 v72, v77 offset:24560
	s_branch .LBB0_304
.Lpw_g3:
	v_lshl_add_u32 v71, v2, 8, v0
	ds_read_b32 v40, v71
	ds_read_b32 v41, v71 offset:256
	ds_read_b32 v42, v71 offset:512
	ds_read_b32 v43, v71 offset:768
	ds_read_b32 v44, v71 offset:1024
	ds_read_b32 v45, v71 offset:1280
	ds_read_b32 v46, v71 offset:1536
	ds_read_b32 v47, v71 offset:1792
	ds_read_b32 v48, v71 offset:2048
	ds_read_b32 v49, v71 offset:2304
	ds_read_b32 v50, v71 offset:2560
	ds_read_b32 v51, v71 offset:2816
	ds_read_b32 v52, v71 offset:3072
	ds_read_b32 v53, v71 offset:3328
	ds_read_b32 v54, v71 offset:3584
	ds_read_b32 v55, v71 offset:3840
	ds_read_b32 v56, v71 offset:4096
	ds_read_b32 v57, v71 offset:4352
	ds_read_b32 v58, v71 offset:4608
	ds_read_b32 v59, v71 offset:4864
	ds_read_b32 v60, v71 offset:5120
	ds_read_b32 v61, v71 offset:5376
	ds_read_b32 v62, v71 offset:5632
	ds_read_b32 v63, v71 offset:5888
	ds_read_b32 v64, v71 offset:6144
	ds_read_b32 v65, v71 offset:6400
	ds_read_b32 v66, v71 offset:6656
	ds_read_b32 v67, v71 offset:6912
	ds_read_b32 v68, v71 offset:7168
	ds_read_b32 v69, v71 offset:7424
	ds_read_b32 v70, v71 offset:7680
	v_mad_u32_u24 v72, v2, s30, v0
	v_add_u32_e32 v73, s26, v2
	s_waitcnt lgkmcnt(0)
	v_subrev_u32_e32 v75, s6, v73
	v_add_u32_e32 v76, s6, v73
	v_max_i32_e32 v75, 0, v75
	v_min_i32_e32 v76, 0x2000, v76
	v_sub_u32_e32 v75, v76, v75
	v_cvt_f32_i32_e32 v75, v75
	v_rcp_iflag_f32_e32 v75, v75
	v_add_f32_e32 v77, 0, v40
	v_add_f32_e32 v77, v77, v41
	v_add_f32_e32 v77, v77, v42
	v_add_f32_e32 v77, v77, v43
	v_add_f32_e32 v77, v77, v44
	v_add_f32_e32 v77, v77, v45
	v_add_f32_e32 v77, v77, v46
	v_add_f32_e32 v77, v77, v47
	v_add_f32_e32 v77, v77, v48
	v_add_f32_e32 v77, v77, v49
	v_add_f32_e32 v77, v77, v50
	v_add_f32_e32 v77, v77, v51
	v_add_f32_e32 v77, v77, v52
	v_add_f32_e32 v77, v77, v53
	v_add_f32_e32 v77, v77, v54
	v_add_f32_e32 v77, v77, v55
	v_fma_f32 v77, v75, v77, -v48
	ds_write_b32 v72, v77 offset:20480
	v_add_u32_e32 v74, 1, v73
	v_subrev_u32_e32 v75, s6, v74
	v_add_u32_e32 v76, s6, v74
	v_max_i32_e32 v75, 0, v75
	v_min_i32_e32 v76, 0x2000, v76
	v_sub_u32_e32 v75, v76, v75
	v_cvt_f32_i32_e32 v75, v75
	v_rcp_iflag_f32_e32 v75, v75
	v_add_f32_e32 v77, 0, v41
	v_add_f32_e32 v77, v77, v42
	v_add_f32_e32 v77, v77, v43
	v_add_f32_e32 v77, v77, v44
	v_add_f32_e32 v77, v77, v45
	v_add_f32_e32 v77, v77, v46
	v_add_f32_e32 v77, v77, v47
	v_add_f32_e32 v77, v77, v48
	v_add_f32_e32 v77, v77, v49
	v_add_f32_e32 v77, v77, v50
	v_add_f32_e32 v77, v77, v51
	v_add_f32_e32 v77, v77, v52
	v_add_f32_e32 v77, v77, v53
	v_add_f32_e32 v77, v77, v54
	v_add_f32_e32 v77, v77, v55
	v_add_f32_e32 v77, v77, v56
	v_fma_f32 v77, v75, v77, -v49
	ds_write_b32 v72, v77 offset:20752
	v_add_u32_e32 v74, 2, v73
	v_subrev_u32_e32 v75, s6, v74
	v_add_u32_e32 v76, s6, v74
	v_max_i32_e32 v75, 0, v75
	v_min_i32_e32 v76, 0x2000, v76
	v_sub_u32_e32 v75, v76, v75
; DI void pool_item(const Params& p, int layer, int seq, int tile, int g, char* smem) {
;     ...
;     const int e = tid & 63, tq = tid >> 6;
; #pragma unroll 4
;     for (int i = 0; i < 16; ++i) {
;         const int tt = tq * 16 + i, t = t0 + tt;
;         const int lo = t - w2 < 0 ? 0 : t - w2, hi = t + w2 > Ls ? Ls : t + w2;
;         float s = 0.f;
;         for (int q = lo; q < hi; ++q) s += su[(q - t0 + 8) * 64 + e];
;         sd[tt * 68 + e] = s * __builtin_amdgcn_rcpf((float)(hi - lo)) - su[(tt + 8) * 64 + e];
;     }
	v_cvt_f32_i32_e32 v75, v75
	v_rcp_iflag_f32_e32 v75, v75
	v_add_f32_e32 v77, 0, v42
	v_add_f32_e32 v77, v77, v43
	v_add_f32_e32 v77, v77, v44
	v_add_f32_e32 v77, v77, v45
	v_add_f32_e32 v77, v77, v46
	v_add_f32_e32 v77, v77, v47
	v_add_f32_e32 v77, v77, v48
	v_add_f32_e32 v77, v77, v49
	v_add_f32_e32 v77, v77, v50
	v_add_f32_e32 v77, v77, v51
	v_add_f32_e32 v77, v77, v52
	v_add_f32_e32 v77, v77, v53
	v_add_f32_e32 v77, v77, v54
	v_add_f32_e32 v77, v77, v55
	v_add_f32_e32 v77, v77, v56
	v_add_f32_e32 v77, v77, v57
	v_fma_f32 v77, v75, v77, -v50
	ds_write_b32 v72, v77 offset:21024
	v_add_u32_e32 v74, 3, v73
	v_subrev_u32_e32 v75, s6, v74
	v_add_u32_e32 v76, s6, v74
	v_max_i32_e32 v75, 0, v75
	v_min_i32_e32 v76, 0x2000, v76
	v_sub_u32_e32 v75, v76, v75
	v_cvt_f32_i32_e32 v75, v75
	v_rcp_iflag_f32_e32 v75, v75
	v_add_f32_e32 v77, 0, v43
	v_add_f32_e32 v77, v77, v44
	v_add_f32_e32 v77, v77, v45
	v_add_f32_e32 v77, v77, v46
	v_add_f32_e32 v77, v77, v47
	v_add_f32_e32 v77, v77, v48
	v_add_f32_e32 v77, v77, v49
	v_add_f32_e32 v77, v77, v50
	v_add_f32_e32 v77, v77, v51
	v_add_f32_e32 v77, v77, v52
	v_add_f32_e32 v77, v77, v53
	v_add_f32_e32 v77, v77, v54
	v_add_f32_e32 v77, v77, v55
	v_add_f32_e32 v77, v77, v56
	v_add_f32_e32 v77, v77, v57
	v_add_f32_e32 v77, v77, v58
	v_fma_f32 v77, v75, v77, -v51
	ds_write_b32 v72, v77 offset:21296
	v_add_u32_e32 v74, 4, v73
	v_subrev_u32_e32 v75, s6, v74
	v_add_u32_e32 v76, s6, v74
	v_max_i32_e32 v75, 0, v75
	v_min_i32_e32 v76, 0x2000, v76
	v_sub_u32_e32 v75, v76, v75
	v_cvt_f32_i32_e32 v75, v75
	v_rcp_iflag_f32_e32 v75, v75
	v_add_f32_e32 v77, 0, v44
	v_add_f32_e32 v77, v77, v45
	v_add_f32_e32 v77, v77, v46
	v_add_f32_e32 v77, v77, v47
	v_add_f32_e32 v77, v77, v48
	v_add_f32_e32 v77, v77, v49
	v_add_f32_e32 v77, v77, v50
	v_add_f32_e32 v77, v77, v51
	v_add_f32_e32 v77, v77, v52
	v_add_f32_e32 v77, v77, v53
	v_add_f32_e32 v77, v77, v54
	v_add_f32_e32 v77, v77, v55
	v_add_f32_e32 v77, v77, v56
	v_add_f32_e32 v77, v77, v57
	v_add_f32_e32 v77, v77, v58
	v_add_f32_e32 v77, v77, v59
	v_fma_f32 v77, v75, v77, -v52
	ds_write_b32 v72, v77 offset:21568
	v_add_u32_e32 v74, 5, v73
	v_subrev_u32_e32 v75, s6, v74
	v_add_u32_e32 v76, s6, v74
	v_max_i32_e32 v75, 0, v75
	v_min_i32_e32 v76, 0x2000, v76
	v_sub_u32_e32 v75, v76, v75
	v_cvt_f32_i32_e32 v75, v75
	v_rcp_iflag_f32_e32 v75, v75
	v_add_f32_e32 v77, 0, v45
	v_add_f32_e32 v77, v77, v46
	v_add_f32_e32 v77, v77, v47
	v_add_f32_e32 v77, v77, v48
	v_add_f32_e32 v77, v77, v49
	v_add_f32_e32 v77, v77, v50
	v_add_f32_e32 v77, v77, v51
	v_add_f32_e32 v77, v77, v52
	v_add_f32_e32 v77, v77, v53
	v_add_f32_e32 v77, v77, v54
	v_add_f32_e32 v77, v77, v55
	v_add_f32_e32 v77, v77, v56
	v_add_f32_e32 v77, v77, v57
	v_add_f32_e32 v77, v77, v58
	v_add_f32_e32 v77, v77, v59
	v_add_f32_e32 v77, v77, v60
	v_fma_f32 v77, v75, v77, -v53
	ds_write_b32 v72, v77 offset:21840
	v_add_u32_e32 v74, 6, v73
	v_subrev_u32_e32 v75, s6, v74
	v_add_u32_e32 v76, s6, v74
	v_max_i32_e32 v75, 0, v75
	v_min_i32_e32 v76, 0x2000, v76
	v_sub_u32_e32 v75, v76, v75
	v_cvt_f32_i32_e32 v75, v75
	v_rcp_iflag_f32_e32 v75, v75
	v_add_f32_e32 v77, 0, v46
	v_add_f32_e32 v77, v77, v47
	v_add_f32_e32 v77, v77, v48
	v_add_f32_e32 v77, v77, v49
	v_add_f32_e32 v77, v77, v50
	v_add_f32_e32 v77, v77, v51
	v_add_f32_e32 v77, v77, v52
	v_add_f32_e32 v77, v77, v53
	v_add_f32_e32 v77, v77, v54
	v_add_f32_e32 v77, v77, v55
	v_add_f32_e32 v77, v77, v56
	v_add_f32_e32 v77, v77, v57
	v_add_f32_e32 v77, v77, v58
	v_add_f32_e32 v77, v77, v59
	v_add_f32_e32 v77, v77, v60
	v_add_f32_e32 v77, v77, v61
	v_fma_f32 v77, v75, v77, -v54
	ds_write_b32 v72, v77 offset:22112
	v_add_u32_e32 v74, 7, v73
	v_subrev_u32_e32 v75, s6, v74
	v_add_u32_e32 v76, s6, v74
	v_max_i32_e32 v75, 0, v75
	v_min_i32_e32 v76, 0x2000, v76
	v_sub_u32_e32 v75, v76, v75
	v_cvt_f32_i32_e32 v75, v75
	v_rcp_iflag_f32_e32 v75, v75
	v_add_f32_e32 v77, 0, v47
	v_add_f32_e32 v77, v77, v48
	v_add_f32_e32 v77, v77, v49
	v_add_f32_e32 v77, v77, v50
	v_add_f32_e32 v77, v77, v51
	v_add_f32_e32 v77, v77, v52
	v_add_f32_e32 v77, v77, v53
	v_add_f32_e32 v77, v77, v54
	v_add_f32_e32 v77, v77, v55
	v_add_f32_e32 v77, v77, v56
	v_add_f32_e32 v77, v77, v57
	v_add_f32_e32 v77, v77, v58
	v_add_f32_e32 v77, v77, v59
	v_add_f32_e32 v77, v77, v60
	v_add_f32_e32 v77, v77, v61
	v_add_f32_e32 v77, v77, v62
	v_fma_f32 v77, v75, v77, -v55
	ds_write_b32 v72, v77 offset:22384
	v_add_u32_e32 v74, 8, v73
	v_subrev_u32_e32 v75, s6, v74
	v_add_u32_e32 v76, s6, v74
	v_max_i32_e32 v75, 0, v75
	v_min_i32_e32 v76, 0x2000, v76
	v_sub_u32_e32 v75, v76, v75
	v_cvt_f32_i32_e32 v75, v75
	v_rcp_iflag_f32_e32 v75, v75
	v_add_f32_e32 v77, 0, v48
	v_add_f32_e32 v77, v77, v49
	v_add_f32_e32 v77, v77, v50
	v_add_f32_e32 v77, v77, v51
	v_add_f32_e32 v77, v77, v52
	v_add_f32_e32 v77, v77, v53
	v_add_f32_e32 v77, v77, v54
	v_add_f32_e32 v77, v77, v55
	v_add_f32_e32 v77, v77, v56
	v_add_f32_e32 v77, v77, v57
	v_add_f32_e32 v77, v77, v58
	v_add_f32_e32 v77, v77, v59
	v_add_f32_e32 v77, v77, v60
	v_add_f32_e32 v77, v77, v61
	v_add_f32_e32 v77, v77, v62
	v_add_f32_e32 v77, v77, v63
	v_fma_f32 v77, v75, v77, -v56
	ds_write_b32 v72, v77 offset:22656
	v_add_u32_e32 v74, 9, v73
	v_subrev_u32_e32 v75, s6, v74
	v_add_u32_e32 v76, s6, v74
; DI void pool_item(const Params& p, int layer, int seq, int tile, int g, char* smem) {
;     ...
;     const int e = tid & 63, tq = tid >> 6;
; #pragma unroll 4
;     for (int i = 0; i < 16; ++i) {
;         const int tt = tq * 16 + i, t = t0 + tt;
;         const int lo = t - w2 < 0 ? 0 : t - w2, hi = t + w2 > Ls ? Ls : t + w2;
;         float s = 0.f;
;         for (int q = lo; q < hi; ++q) s += su[(q - t0 + 8) * 64 + e];
;         sd[tt * 68 + e] = s * __builtin_amdgcn_rcpf((float)(hi - lo)) - su[(tt + 8) * 64 + e];
;     }
	v_max_i32_e32 v75, 0, v75
	v_min_i32_e32 v76, 0x2000, v76
	v_sub_u32_e32 v75, v76, v75
	v_cvt_f32_i32_e32 v75, v75
	v_rcp_iflag_f32_e32 v75, v75
	v_add_f32_e32 v77, 0, v49
	v_add_f32_e32 v77, v77, v50
	v_add_f32_e32 v77, v77, v51
	v_add_f32_e32 v77, v77, v52
	v_add_f32_e32 v77, v77, v53
	v_add_f32_e32 v77, v77, v54
	v_add_f32_e32 v77, v77, v55
	v_add_f32_e32 v77, v77, v56
	v_add_f32_e32 v77, v77, v57
	v_add_f32_e32 v77, v77, v58
	v_add_f32_e32 v77, v77, v59
	v_add_f32_e32 v77, v77, v60
	v_add_f32_e32 v77, v77, v61
	v_add_f32_e32 v77, v77, v62
	v_add_f32_e32 v77, v77, v63
	v_add_f32_e32 v77, v77, v64
	v_fma_f32 v77, v75, v77, -v57
	ds_write_b32 v72, v77 offset:22928
	v_add_u32_e32 v74, 10, v73
	v_subrev_u32_e32 v75, s6, v74
	v_add_u32_e32 v76, s6, v74
	v_max_i32_e32 v75, 0, v75
	v_min_i32_e32 v76, 0x2000, v76
	v_sub_u32_e32 v75, v76, v75
	v_cvt_f32_i32_e32 v75, v75
	v_rcp_iflag_f32_e32 v75, v75
	v_add_f32_e32 v77, 0, v50
	v_add_f32_e32 v77, v77, v51
	v_add_f32_e32 v77, v77, v52
	v_add_f32_e32 v77, v77, v53
	v_add_f32_e32 v77, v77, v54
	v_add_f32_e32 v77, v77, v55
	v_add_f32_e32 v77, v77, v56
	v_add_f32_e32 v77, v77, v57
	v_add_f32_e32 v77, v77, v58
	v_add_f32_e32 v77, v77, v59
	v_add_f32_e32 v77, v77, v60
	v_add_f32_e32 v77, v77, v61
	v_add_f32_e32 v77, v77, v62
	v_add_f32_e32 v77, v77, v63
	v_add_f32_e32 v77, v77, v64
	v_add_f32_e32 v77, v77, v65
	v_fma_f32 v77, v75, v77, -v58
	ds_write_b32 v72, v77 offset:23200
	v_add_u32_e32 v74, 11, v73
	v_subrev_u32_e32 v75, s6, v74
	v_add_u32_e32 v76, s6, v74
	v_max_i32_e32 v75, 0, v75
	v_min_i32_e32 v76, 0x2000, v76
	v_sub_u32_e32 v75, v76, v75
	v_cvt_f32_i32_e32 v75, v75
	v_rcp_iflag_f32_e32 v75, v75
	v_add_f32_e32 v77, 0, v51
	v_add_f32_e32 v77, v77, v52
	v_add_f32_e32 v77, v77, v53
	v_add_f32_e32 v77, v77, v54
	v_add_f32_e32 v77, v77, v55
	v_add_f32_e32 v77, v77, v56
	v_add_f32_e32 v77, v77, v57
	v_add_f32_e32 v77, v77, v58
	v_add_f32_e32 v77, v77, v59
	v_add_f32_e32 v77, v77, v60
	v_add_f32_e32 v77, v77, v61
	v_add_f32_e32 v77, v77, v62
	v_add_f32_e32 v77, v77, v63
	v_add_f32_e32 v77, v77, v64
	v_add_f32_e32 v77, v77, v65
	v_add_f32_e32 v77, v77, v66
	v_fma_f32 v77, v75, v77, -v59
	ds_write_b32 v72, v77 offset:23472
	v_add_u32_e32 v74, 12, v73
	v_subrev_u32_e32 v75, s6, v74
	v_add_u32_e32 v76, s6, v74
	v_max_i32_e32 v75, 0, v75
	v_min_i32_e32 v76, 0x2000, v76
	v_sub_u32_e32 v75, v76, v75
	v_cvt_f32_i32_e32 v75, v75
	v_rcp_iflag_f32_e32 v75, v75
	v_add_f32_e32 v77, 0, v52
	v_add_f32_e32 v77, v77, v53
	v_add_f32_e32 v77, v77, v54
	v_add_f32_e32 v77, v77, v55
	v_add_f32_e32 v77, v77, v56
	v_add_f32_e32 v77, v77, v57
	v_add_f32_e32 v77, v77, v58
	v_add_f32_e32 v77, v77, v59
	v_add_f32_e32 v77, v77, v60
	v_add_f32_e32 v77, v77, v61
	v_add_f32_e32 v77, v77, v62
	v_add_f32_e32 v77, v77, v63
	v_add_f32_e32 v77, v77, v64
	v_add_f32_e32 v77, v77, v65
	v_add_f32_e32 v77, v77, v66
	v_add_f32_e32 v77, v77, v67
	v_fma_f32 v77, v75, v77, -v60
	ds_write_b32 v72, v77 offset:23744
	v_add_u32_e32 v74, 13, v73
	v_subrev_u32_e32 v75, s6, v74
	v_add_u32_e32 v76, s6, v74
	v_max_i32_e32 v75, 0, v75
	v_min_i32_e32 v76, 0x2000, v76
	v_sub_u32_e32 v75, v76, v75
	v_cvt_f32_i32_e32 v75, v75
	v_rcp_iflag_f32_e32 v75, v75
	v_add_f32_e32 v77, 0, v53
	v_add_f32_e32 v77, v77, v54
	v_add_f32_e32 v77, v77, v55
	v_add_f32_e32 v77, v77, v56
	v_add_f32_e32 v77, v77, v57
	v_add_f32_e32 v77, v77, v58
	v_add_f32_e32 v77, v77, v59
	v_add_f32_e32 v77, v77, v60
	v_add_f32_e32 v77, v77, v61
	v_add_f32_e32 v77, v77, v62
	v_add_f32_e32 v77, v77, v63
	v_add_f32_e32 v77, v77, v64
	v_add_f32_e32 v77, v77, v65
	v_add_f32_e32 v77, v77, v66
	v_add_f32_e32 v77, v77, v67
	v_add_f32_e32 v77, v77, v68
	v_fma_f32 v77, v75, v77, -v61
	ds_write_b32 v72, v77 offset:24016
	v_add_u32_e32 v74, 14, v73
	v_subrev_u32_e32 v75, s6, v74
	v_add_u32_e32 v76, s6, v74
	v_max_i32_e32 v75, 0, v75
	v_min_i32_e32 v76, 0x2000, v76
	v_sub_u32_e32 v75, v76, v75
	v_cvt_f32_i32_e32 v75, v75
	v_rcp_iflag_f32_e32 v75, v75
	v_add_f32_e32 v77, 0, v54
	v_add_f32_e32 v77, v77, v55
	v_add_f32_e32 v77, v77, v56
	v_add_f32_e32 v77, v77, v57
	v_add_f32_e32 v77, v77, v58
	v_add_f32_e32 v77, v77, v59
	v_add_f32_e32 v77, v77, v60
	v_add_f32_e32 v77, v77, v61
	v_add_f32_e32 v77, v77, v62
	v_add_f32_e32 v77, v77, v63
	v_add_f32_e32 v77, v77, v64
	v_add_f32_e32 v77, v77, v65
	v_add_f32_e32 v77, v77, v66
	v_add_f32_e32 v77, v77, v67
	v_add_f32_e32 v77, v77, v68
	v_add_f32_e32 v77, v77, v69
	v_fma_f32 v77, v75, v77, -v62
	ds_write_b32 v72, v77 offset:24288
	v_add_u32_e32 v74, 15, v73
	v_subrev_u32_e32 v75, s6, v74
	v_add_u32_e32 v76, s6, v74
	v_max_i32_e32 v75, 0, v75
	v_min_i32_e32 v76, 0x2000, v76
	v_sub_u32_e32 v75, v76, v75
	v_cvt_f32_i32_e32 v75, v75
	v_rcp_iflag_f32_e32 v75, v75
	v_add_f32_e32 v77, 0, v55
	v_add_f32_e32 v77, v77, v56
	v_add_f32_e32 v77, v77, v57
	v_add_f32_e32 v77, v77, v58
	v_add_f32_e32 v77, v77, v59
	v_add_f32_e32 v77, v77, v60
	v_add_f32_e32 v77, v77, v61
	v_add_f32_e32 v77, v77, v62
	v_add_f32_e32 v77, v77, v63
	v_add_f32_e32 v77, v77, v64
	v_add_f32_e32 v77, v77, v65
	v_add_f32_e32 v77, v77, v66
	v_add_f32_e32 v77, v77, v67
	v_add_f32_e32 v77, v77, v68
	v_add_f32_e32 v77, v77, v69
	v_add_f32_e32 v77, v77, v70
	v_fma_f32 v77, v75, v77, -v63
	ds_write_b32 v72, v77 offset:24560
